# pipelined attention v8: 16 chain-0 exps issued speculatively between the dependent levels of the row-max tree; rare rescale path multiplies them by 2^-delta
# speedup vs baseline: 1.0441x; 1.0067x over previous
; DI float xor32_max(float x) { auto r = __builtin_amdgcn_permlane32_swap(__float_as_uint(x), __float_as_uint(x), false, false); return fmaxf(__uint_as_float(r[0]), __uint_as_float(r[1])); }
; DI float max3f(float a, float b, float c) { float r; asm("v_max3_f32 %0, %1, %2, %3" : "=v"(r) : "v"(a), "v"(b), "v"(c)); return r; }
; DI void attn_s(const unsigned char* sK, int tt, int qb, int qs, int sub, int l31, int h,
;                const bf16x8 (&qf)[4], f32x16 (&O)[4], float& m, float& l, bf16x8 (&pb)[4]) {
;     ...
;     float mx;
;     {
;         float t[11];
; #pragma unroll
;         for (int i = 0; i < 5; ++i) t[i] = max3f(st[0][3 * i], st[0][3 * i + 1], st[0][3 * i + 2]);
; #pragma unroll
;         for (int i = 0; i < 5; ++i) t[5 + i] = max3f(st[1][3 * i], st[1][3 * i + 1], st[1][3 * i + 2]);
;         t[10] = fmaxf(st[0][15], st[1][15]);
;         const float u0 = max3f(t[0], t[1], t[2]), u1 = max3f(t[3], t[4], t[5]), u2 = max3f(t[6], t[7], t[8]);
;         mx = max3f(max3f(u0, u1, u2), t[9], t[10]);
;     }
;     mx = xor32_max(mx);
;     if (tt == 0 || __builtin_amdgcn_ballot_w64(mx > 8.0f) != 0ull) {
;         const float delta = tt == 0 ? mx : fmaxf(mx, 0.f);
;         const float alpha = __builtin_amdgcn_exp2f(-delta);
;         m += delta;
;         l *= alpha;
; #pragma unroll
;         for (int d = 0; d < 4; ++d) O[d] = O[d] * alpha;
; #pragma unroll
;         for (int k2 = 0; k2 < 2; ++k2) st[k2] = st[k2] - delta;
;     }
; #pragma unroll
;     for (int k2 = 0; k2 < 2; ++k2)
; #pragma unroll
;         for (int i = 0; i < 16; ++i) st[k2][i] = __builtin_amdgcn_exp2f(st[k2][i]);
.Lpipe_nomask_l:
	v_max3_f32 v159, v82, v83, v84
	v_max3_f32 v160, v85, v86, v87
	v_max3_f32 v161, v88, v89, v90
	v_max3_f32 v162, v91, v92, v93
	v_max3_f32 v163, v94, v95, v96
	v_max3_f32 v164, v66, v67, v68
	v_max3_f32 v165, v69, v70, v71
	v_max3_f32 v166, v72, v73, v74
	v_max3_f32 v167, v75, v76, v77
	v_max3_f32 v168, v78, v79, v80
	v_max_f32_e32 v169, v81, v81
	v_max_f32_e32 v170, v97, v97
	v_exp_f32_e32 v82, v82
	v_exp_f32_e32 v83, v83
	v_max3_f32 v159, v159, v160, v161
	v_max3_f32 v160, v162, v163, v164
	v_exp_f32_e32 v84, v84
	v_exp_f32_e32 v85, v85
	v_max3_f32 v161, v165, v166, v167
	v_max_f32_e32 v169, v170, v169
	v_exp_f32_e32 v86, v86
	v_exp_f32_e32 v87, v87
	v_max3_f32 v159, v159, v160, v161
	v_exp_f32_e32 v88, v88
	v_exp_f32_e32 v89, v89
	s_mov_b32 s14, 0x41000000
	v_max3_f32 v159, v159, v168, v169
	v_exp_f32_e32 v90, v90
	v_exp_f32_e32 v91, v91
	v_mov_b32_e32 v160, v159
	v_exp_f32_e32 v92, v92
	v_exp_f32_e32 v93, v93
	v_permlane32_swap_b32_e32 v159, v160
	v_exp_f32_e32 v94, v94
	v_exp_f32_e32 v95, v95
	v_max_f32_e32 v160, v160, v160
	v_max_f32_e32 v159, v159, v159
	v_max_f32_e32 v159, v159, v160
	v_exp_f32_e32 v96, v96
	v_exp_f32_e32 v97, v97
	v_cmp_lt_f32_e32 vcc, s14, v159
	s_cbranch_vccz .Lpipe_norescale_l
	v_max_f32_e32 v159, v159, v159
	v_max_f32_e32 v159, 0, v159
	v_exp_f32_e64 v160, -v159
	v_add_f32_e32 v157, v157, v159
	v_xor_b32_e32 v240, 0x80000000, v157
	v_mov_b32_e32 v241, v240
	v_mov_b32_e32 v242, v240
	v_mov_b32_e32 v243, v240
	v_mov_b32_e32 v244, v240
	v_mov_b32_e32 v245, v240
	v_mov_b32_e32 v246, v240
	v_mov_b32_e32 v247, v240
	v_mov_b32_e32 v248, v240
	v_mov_b32_e32 v249, v240
	v_mov_b32_e32 v250, v240
	v_mov_b32_e32 v251, v240
	v_mov_b32_e32 v252, v240
	v_mov_b32_e32 v253, v240
	v_mov_b32_e32 v254, v240
	v_mov_b32_e32 v255, v240
	v_mul_f32_e32 v1, v1, v160
	v_pk_mul_f32 v[64:65], v[64:65], v[160:161] op_sel_hi:[1,0]
	v_pk_mul_f32 v[62:63], v[62:63], v[160:161] op_sel_hi:[1,0]
	v_pk_mul_f32 v[60:61], v[60:61], v[160:161] op_sel_hi:[1,0]
	v_pk_mul_f32 v[58:59], v[58:59], v[160:161] op_sel_hi:[1,0]
	v_pk_mul_f32 v[56:57], v[56:57], v[160:161] op_sel_hi:[1,0]
	v_pk_mul_f32 v[54:55], v[54:55], v[160:161] op_sel_hi:[1,0]
	v_pk_mul_f32 v[52:53], v[52:53], v[160:161] op_sel_hi:[1,0]
	v_pk_mul_f32 v[50:51], v[50:51], v[160:161] op_sel_hi:[1,0]
	v_pk_mul_f32 v[48:49], v[48:49], v[160:161] op_sel_hi:[1,0]
	v_pk_mul_f32 v[46:47], v[46:47], v[160:161] op_sel_hi:[1,0]
	v_pk_mul_f32 v[44:45], v[44:45], v[160:161] op_sel_hi:[1,0]
	v_pk_mul_f32 v[42:43], v[42:43], v[160:161] op_sel_hi:[1,0]
	v_pk_mul_f32 v[40:41], v[40:41], v[160:161] op_sel_hi:[1,0]
	v_pk_mul_f32 v[38:39], v[38:39], v[160:161] op_sel_hi:[1,0]
	v_pk_mul_f32 v[36:37], v[36:37], v[160:161] op_sel_hi:[1,0]
	v_pk_mul_f32 v[34:35], v[34:35], v[160:161] op_sel_hi:[1,0]
	v_pk_mul_f32 v[32:33], v[32:33], v[160:161] op_sel_hi:[1,0]
	v_pk_mul_f32 v[30:31], v[30:31], v[160:161] op_sel_hi:[1,0]
	v_pk_mul_f32 v[28:29], v[28:29], v[160:161] op_sel_hi:[1,0]
	v_pk_mul_f32 v[26:27], v[26:27], v[160:161] op_sel_hi:[1,0]
	v_pk_mul_f32 v[24:25], v[24:25], v[160:161] op_sel_hi:[1,0]
	v_pk_mul_f32 v[22:23], v[22:23], v[160:161] op_sel_hi:[1,0]
	v_pk_mul_f32 v[20:21], v[20:21], v[160:161] op_sel_hi:[1,0]
	v_pk_mul_f32 v[18:19], v[18:19], v[160:161] op_sel_hi:[1,0]
	v_pk_mul_f32 v[16:17], v[16:17], v[160:161] op_sel_hi:[1,0]
	v_pk_mul_f32 v[14:15], v[14:15], v[160:161] op_sel_hi:[1,0]
	v_pk_mul_f32 v[12:13], v[12:13], v[160:161] op_sel_hi:[1,0]
	v_pk_mul_f32 v[10:11], v[10:11], v[160:161] op_sel_hi:[1,0]
	v_pk_mul_f32 v[8:9], v[8:9], v[160:161] op_sel_hi:[1,0]
	v_pk_mul_f32 v[6:7], v[6:7], v[160:161] op_sel_hi:[1,0]
	v_pk_mul_f32 v[4:5], v[4:5], v[160:161] op_sel_hi:[1,0]
	v_pk_mul_f32 v[2:3], v[2:3], v[160:161] op_sel_hi:[1,0]
	v_mul_f32_e32 v82, v82, v160
	v_mul_f32_e32 v83, v83, v160
	v_mul_f32_e32 v84, v84, v160
	v_mul_f32_e32 v85, v85, v160
	v_mul_f32_e32 v86, v86, v160
	v_mul_f32_e32 v87, v87, v160
	v_mul_f32_e32 v88, v88, v160
	v_mul_f32_e32 v89, v89, v160
	v_mul_f32_e32 v90, v90, v160
	v_mul_f32_e32 v91, v91, v160
	v_mul_f32_e32 v92, v92, v160
	v_mul_f32_e32 v93, v93, v160
	v_mul_f32_e32 v94, v94, v160
	v_mul_f32_e32 v95, v95, v160
	v_mul_f32_e32 v96, v96, v160
	v_mul_f32_e32 v97, v97, v160
	v_sub_f32_e32 v66, v66, v159
	v_sub_f32_e32 v67, v67, v159
	v_sub_f32_e32 v68, v68, v159
	v_sub_f32_e32 v69, v69, v159
	v_sub_f32_e32 v70, v70, v159
	v_sub_f32_e32 v71, v71, v159
	v_sub_f32_e32 v72, v72, v159
	v_sub_f32_e32 v73, v73, v159
	v_sub_f32_e32 v74, v74, v159
	v_sub_f32_e32 v75, v75, v159
	v_sub_f32_e32 v76, v76, v159
	v_sub_f32_e32 v77, v77, v159
	v_sub_f32_e32 v78, v78, v159
	v_sub_f32_e32 v79, v79, v159
	v_sub_f32_e32 v80, v80, v159
	v_sub_f32_e32 v81, v81, v159
; #define MFMA32(a, b, c) __builtin_amdgcn_mfma_f32_32x32x16_bf16((a), (b), (c), 0, 0, 0)
; DI unsigned pk2(float a, float b) { f32x2 v = {a, b}; return __builtin_bit_cast(unsigned, __builtin_convertvector(v, bfv2)); }
; DI void attn_s(const unsigned char* sK, int tt, int qb, int qs, int sub, int l31, int h,
;                const bf16x8 (&qf)[4], f32x16 (&O)[4], float& m, float& l, bf16x8 (&pb)[4]) {
;     ...
; #pragma unroll
;     for (int k2 = 0; k2 < 2; ++k2)
; #pragma unroll
;         for (int i = 0; i < 16; ++i) st[k2][i] = __builtin_amdgcn_exp2f(st[k2][i]);
;     {
;         const f32x16 sv = st[0] + st[1];
;         const float ps = (((sv[0] + sv[1]) + (sv[2] + sv[3])) + ((sv[4] + sv[5]) + (sv[6] + sv[7]))) + (((sv[8] + sv[9]) + (sv[10] + sv[11])) + ((sv[12] + sv[13]) + (sv[14] + sv[15])));
;         l += ps;
;     }
; #pragma unroll
;     for (int k4 = 0; k4 < 4; ++k4) {
;         const int k2 = k4 >> 1, o8 = 8 * (k4 & 1);
;         u32x4 pk;
;         pk.x = pk2(st[k2][o8 + 0], st[k2][o8 + 1]); pk.y = pk2(st[k2][o8 + 2], st[k2][o8 + 3]);
;         pk.z = pk2(st[k2][o8 + 4], st[k2][o8 + 5]); pk.w = pk2(st[k2][o8 + 6], st[k2][o8 + 7]);
;         pb[k4] = __builtin_bit_cast(bf16x8, pk);
;     }
; DI void attn_pv(const unsigned char* sV, int l31, int h, const bf16x8 (&pb)[4], f32x16 (&O)[4]) {
;     ...
;         for (int d = 0; d < 4; ++d) O[d] = MFMA32(va[d], pb[0], O[d]);
;         __builtin_amdgcn_sched_barrier(0);
; #pragma unroll
;         for (int d = 0; d < 4; ++d) va[d] = *(const bf16x8*)(vb + d * 32 * A_VROWB + 64);
;         __builtin_amdgcn_sched_barrier(0);
; #pragma unroll
;         for (int d = 0; d < 4; ++d) O[d] = MFMA32(vc[d], pb[1], O[d]);
;         __builtin_amdgcn_sched_barrier(0);
; #pragma unroll
;         for (int d = 0; d < 4; ++d) vc[d] = *(const bf16x8*)(vb + d * 32 * A_VROWB + 96);
;         __builtin_amdgcn_sched_barrier(0);
; #pragma unroll
;         for (int d = 0; d < 4; ++d) O[d] = MFMA32(va[d], pb[2], O[d]);
;         __builtin_amdgcn_sched_barrier(0);
; #pragma unroll
;         for (int d = 0; d < 4; ++d) O[d] = MFMA32(vc[d], pb[3], O[d]);
.Lpipe_norescale_l:
	v_exp_f32_e32 v66, v66
	v_exp_f32_e32 v67, v67
	v_exp_f32_e32 v68, v68
	v_exp_f32_e32 v69, v69
	v_exp_f32_e32 v70, v70
	v_exp_f32_e32 v71, v71
	v_exp_f32_e32 v72, v72
	v_exp_f32_e32 v73, v73
	v_exp_f32_e32 v74, v74
	v_exp_f32_e32 v75, v75
	v_exp_f32_e32 v76, v76
	v_exp_f32_e32 v77, v77
	v_exp_f32_e32 v78, v78
	v_exp_f32_e32 v79, v79
	v_exp_f32_e32 v80, v80
	v_exp_f32_e32 v81, v81
	v_cvt_pk_bf16_f32 v216, v82, v83
	v_cvt_pk_bf16_f32 v217, v84, v85
	v_cvt_pk_bf16_f32 v218, v86, v87
	v_cvt_pk_bf16_f32 v219, v88, v89
	v_cvt_pk_bf16_f32 v220, v90, v91
	v_cvt_pk_bf16_f32 v221, v92, v93
	v_cvt_pk_bf16_f32 v222, v94, v95
	v_cvt_pk_bf16_f32 v223, v96, v97
	v_cvt_pk_bf16_f32 v224, v66, v67
	v_cvt_pk_bf16_f32 v225, v68, v69
	v_cvt_pk_bf16_f32 v226, v70, v71
	v_cvt_pk_bf16_f32 v227, v72, v73
	v_cvt_pk_bf16_f32 v228, v74, v75
	v_cvt_pk_bf16_f32 v229, v76, v77
	v_cvt_pk_bf16_f32 v230, v78, v79
	v_cvt_pk_bf16_f32 v231, v80, v81
	v_pk_add_f32 v[68:69], v[84:85], v[68:69]
	v_pk_add_f32 v[66:67], v[82:83], v[66:67]
	v_pk_add_f32 v[72:73], v[88:89], v[72:73]
	v_pk_add_f32 v[70:71], v[86:87], v[70:71]
	v_add_f32_e32 v66, v66, v67
	v_add_f32_e32 v67, v68, v69
	v_add_f32_e32 v66, v66, v67
	v_add_f32_e32 v67, v70, v71
	v_add_f32_e32 v68, v72, v73
	v_pk_add_f32 v[76:77], v[92:93], v[76:77]
	v_pk_add_f32 v[74:75], v[90:91], v[74:75]
	v_add_f32_e32 v67, v67, v68
	v_pk_add_f32 v[80:81], v[96:97], v[80:81]
	v_pk_add_f32 v[78:79], v[94:95], v[78:79]
	v_add_f32_e32 v66, v66, v67
	v_add_f32_e32 v67, v74, v75
	v_add_f32_e32 v68, v76, v77
	v_add_f32_e32 v67, v67, v68
	v_add_f32_e32 v68, v78, v79
	v_add_f32_e32 v69, v80, v81
	v_add_f32_e32 v68, v68, v69
	v_add_f32_e32 v67, v67, v68
	v_add_f32_e32 v66, v66, v67
	v_add_f32_e32 v1, v1, v66
	v_add_u32_e32 v158, 64, v158
	s_mov_b32 s13, s7
	s_add_i32 s4, s7, 1
	s_cmp_lg_u32 s7, 2
	s_cselect_b32 s7, s4, 0
	s_add_i32 s12, s12, 1
	s_cmp_eq_u32 s11, s12
	s_cbranch_scc1 .Lpipe_final
	s_barrier
	s_setprio 1
	s_mul_i32 s98, s13, 0x8c00
	v_add3_u32 v185, s98, v155, v154
	ds_read_b128 v[160:163], v185
	ds_read_b128 v[164:167], v185 offset:32
	ds_read_b128 v[168:171], v185 offset:8704
	ds_read_b128 v[196:199], v185 offset:8736
	s_waitcnt lgkmcnt(11)
	v_mfma_f32_32x32x16_bf16 v[50:65], v[172:175], v[216:219], v[50:65]
	s_waitcnt lgkmcnt(10)
	v_mfma_f32_32x32x16_bf16 v[34:49], v[176:179], v[216:219], v[34:49]
	s_waitcnt lgkmcnt(9)
	v_mfma_f32_32x32x16_bf16 v[18:33], v[180:183], v[216:219], v[18:33]
	s_waitcnt lgkmcnt(8)
	v_mfma_f32_32x32x16_bf16 v[2:17], v[192:195], v[216:219], v[2:17]
	ds_read_b128 v[172:175], v185 offset:64
	ds_read_b128 v[176:179], v185 offset:96
	ds_read_b128 v[180:183], v185 offset:8768
	ds_read_b128 v[192:195], v185 offset:8800
	s_waitcnt lgkmcnt(11)
	v_mfma_f32_32x32x16_bf16 v[50:65], v[200:203], v[220:223], v[50:65]
	s_waitcnt lgkmcnt(10)
	v_mfma_f32_32x32x16_bf16 v[34:49], v[204:207], v[220:223], v[34:49]
	s_waitcnt lgkmcnt(9)
	v_mfma_f32_32x32x16_bf16 v[18:33], v[208:211], v[220:223], v[18:33]
	s_waitcnt lgkmcnt(8)
	v_mfma_f32_32x32x16_bf16 v[2:17], v[212:215], v[220:223], v[2:17]
	ds_read_b128 v[200:203], v191 offset:17472
	ds_read_b128 v[204:207], v191 offset:22080
	ds_read_b128 v[208:211], v191 offset:26688
	ds_read_b128 v[212:215], v191 offset:31296
	s_waitcnt lgkmcnt(11)
	v_mfma_f32_32x32x16_bf16 v[82:97], v[160:163], v[100:103], v[240:255]
	s_waitcnt lgkmcnt(9)
	v_mfma_f32_32x32x16_bf16 v[66:81], v[168:171], v[100:103], v[240:255]
	v_mfma_f32_32x32x16_bf16 v[82:97], v[164:167], v[104:107], v[82:97]
	s_waitcnt lgkmcnt(8)
	v_mfma_f32_32x32x16_bf16 v[66:81], v[196:199], v[104:107], v[66:81]
	ds_read_b128 v[160:163], v191 offset:17504
	ds_read_b128 v[164:167], v191 offset:22112
	ds_read_b128 v[168:171], v191 offset:26720
	ds_read_b128 v[196:199], v191 offset:31328
	s_waitcnt lgkmcnt(11)
	v_mfma_f32_32x32x16_bf16 v[82:97], v[172:175], v[108:111], v[82:97]
	s_waitcnt lgkmcnt(9)
	v_mfma_f32_32x32x16_bf16 v[66:81], v[180:183], v[108:111], v[66:81]
	v_mfma_f32_32x32x16_bf16 v[82:97], v[176:179], v[112:115], v[82:97]
	s_waitcnt lgkmcnt(8)
	v_mfma_f32_32x32x16_bf16 v[66:81], v[192:195], v[112:115], v[66:81]
	s_add_i32 s14, s12, 0x42
	s_cmp_ge_i32 s14, s6
	s_cbranch_scc1 .Lpipe_nost_l
	s_mul_i32 s4, s7, 0x8c00
	s_add_i32 s4, s4, 0
	v_add_u32_e32 v184, s4, v140
	v_add_u32_e32 v185, v184, v139
	v_add_u32_e32 v184, v184, v141
	s_waitcnt vmcnt(3)
	ds_write_b128 v185, v[116:119]
	s_waitcnt vmcnt(2)
	ds_write_b128 v184, v[120:123]
	v_add3_u32 v184, s4, v150, v151
	v_add_u32_e32 v185, v184, v152
	v_add_u32_e32 v184, v184, v153
	v_add_u32_e32 v185, 0x4000, v185
	v_add_u32_e32 v184, 0x4000, v184
	s_waitcnt vmcnt(1)
	ds_write2_b64 v185, v[124:125], v[126:127] offset0:128 offset1:130
	s_waitcnt vmcnt(0)
	ds_write2_b64 v184, v[128:129], v[130:131] offset0:128 offset1:130
